# GLU gated small_gemm units: same 8 rows x 128 B load shape + per-wave LDS transpose as the down projection
# speedup vs baseline: 1.0274x; 1.0073x over previous
.LBB0_103:
	s_ashr_i32 s0, s23, 31
	s_lshr_b32 s0, s0, 27
	s_add_i32 s0, s23, s0
	s_and_b32 s24, s0, 0xffffffe0
	s_ashr_i32 s1, s0, 5
	s_addk_i32 s24, 0x4000
	s_lshl_b32 s25, s1, 10
	s_lshl_b32 s1, s1, 11
	v_or_b32_e32 v6, s24, v176
	s_sub_i32 s0, s8, s25
	s_sub_i32 s1, s19, s1
	v_ashrrev_i32_e32 v7, 31, v6
	s_and_b32 s1, s1, 0xffffff00
	s_and_b32 s0, s0, 0x60
	v_lshlrev_b64 v[6:7], 11, v[6:7]
	s_or_b32 s0, s1, s0
	v_lshl_add_u64 v[62:63], v[2:3], 0, v[6:7]
	v_or_b32_e32 v22, s0, v176
	v_add_co_u32_e64 v72, s[0:1], s93, v62
	v_addc_co_u32_e64 v73, s[0:1], 0, v63, s[0:1]
	v_or_b32_e32 v18, 16, v22
	v_or_b32_e32 v24, 0x80, v22
	v_or_b32_e32 v30, 0x90, v22
	v_ashrrev_i32_e32 v23, 31, v22
	v_ashrrev_i32_e32 v19, 31, v18
	v_ashrrev_i32_e32 v25, 31, v24
	v_ashrrev_i32_e32 v31, 31, v30
	v_lshlrev_b64 v[10:11], 11, v[22:23]
	v_lshlrev_b64 v[18:19], 11, v[18:19]
	v_lshlrev_b64 v[22:23], 11, v[24:25]
	v_lshlrev_b64 v[30:31], 11, v[30:31]
	v_lshl_add_u64 v[64:65], v[4:5], 0, v[10:11]
	v_lshl_add_u64 v[66:67], v[4:5], 0, v[18:19]
	v_lshl_add_u64 v[68:69], v[4:5], 0, v[22:23]
	v_lshl_add_u64 v[70:71], v[4:5], 0, v[30:31]
	v_and_b32_e32 v222, 63, v204
	v_readfirstlane_b32 s98, v204
	s_lshr_b32 s98, s98, 6
	s_mul_i32 s98, s98, 0x3600
	v_and_b32_e32 v223, 15, v222
	v_lshrrev_b32_e32 v224, 4, v222
	v_mul_u32_u24_e32 v251, 0x90, v223
	v_lshl_add_u32 v251, v224, 4, v251
	v_add_u32_e32 v251, s98, v251
	v_lshrrev_b32_e32 v225, 3, v222
	v_and_b32_e32 v226, 7, v222
	v_sub_u32_e32 v252, v225, v223
	v_sub_u32_e32 v227, v226, v224
	v_lshlrev_b32_e32 v252, 11, v252
	v_lshl_add_u32 v252, v227, 4, v252
	v_ashrrev_i32_e32 v253, 31, v252
	v_mul_u32_u24_e32 v250, 0x90, v225
	v_lshl_add_u32 v250, v226, 4, v250
	v_add_u32_e32 v250, s98, v250
	s_movk_i32 s99, 0x4000
	v_lshl_add_u64 v[6:7], v[62:63], 0, v[252:253]
	v_add_co_u32_e64 v8, s[100:101], s99, v6
	s_nop 1
	v_addc_co_u32_e64 v9, s[100:101], 0, v7, s[100:101]
	v_lshl_add_u64 v[10:11], v[72:73], 0, v[252:253]
	v_add_co_u32_e64 v12, s[100:101], s99, v10
	s_nop 1
	v_addc_co_u32_e64 v13, s[100:101], 0, v11, s[100:101]
	v_lshl_add_u64 v[50:51], v[64:65], 0, v[252:253]
	v_add_co_u32_e64 v52, s[100:101], s99, v50
	s_nop 1
	v_addc_co_u32_e64 v53, s[100:101], 0, v51, s[100:101]
	v_lshl_add_u64 v[54:55], v[66:67], 0, v[252:253]
	v_add_co_u32_e64 v56, s[100:101], s99, v54
	s_nop 1
	v_addc_co_u32_e64 v57, s[100:101], 0, v55, s[100:101]
	v_lshl_add_u64 v[58:59], v[68:69], 0, v[252:253]
	v_add_co_u32_e64 v60, s[100:101], s99, v58
	s_nop 1
	v_addc_co_u32_e64 v61, s[100:101], 0, v59, s[100:101]
	v_lshl_add_u64 v[206:207], v[70:71], 0, v[252:253]
	v_add_co_u32_e64 v208, s[100:101], s99, v206
	s_nop 1
	v_addc_co_u32_e64 v209, s[100:101], 0, v207, s[100:101]
	global_load_dwordx4 v[74:77], v[6:7], off
	global_load_dwordx4 v[82:85], v[8:9], off
	global_load_dwordx4 v[90:93], v[10:11], off
	global_load_dwordx4 v[98:101], v[12:13], off
	global_load_dwordx4 v[106:109], v[50:51], off
	global_load_dwordx4 v[114:117], v[52:53], off
	global_load_dwordx4 v[122:125], v[54:55], off
	global_load_dwordx4 v[130:133], v[56:57], off
	global_load_dwordx4 v[162:165], v[58:59], off
	global_load_dwordx4 v[170:173], v[60:61], off
	global_load_dwordx4 v[182:185], v[206:207], off
	global_load_dwordx4 v[214:217], v[208:209], off
	global_load_dwordx4 v[78:81], v[6:7], off offset:128
	global_load_dwordx4 v[86:89], v[8:9], off offset:128
	global_load_dwordx4 v[94:97], v[10:11], off offset:128
	global_load_dwordx4 v[102:105], v[12:13], off offset:128
	global_load_dwordx4 v[110:113], v[50:51], off offset:128
	global_load_dwordx4 v[118:121], v[52:53], off offset:128
	global_load_dwordx4 v[126:129], v[54:55], off offset:128
	global_load_dwordx4 v[134:137], v[56:57], off offset:128
	global_load_dwordx4 v[166:169], v[58:59], off offset:128
	global_load_dwordx4 v[178:181], v[60:61], off offset:128
	global_load_dwordx4 v[210:213], v[206:207], off offset:128
	global_load_dwordx4 v[218:221], v[208:209], off offset:128
	s_waitcnt vmcnt(12)
	s_barrier
	ds_write_b128 v250, v[74:77]
	ds_write_b128 v250, v[82:85] offset:1152
	ds_write_b128 v250, v[90:93] offset:2304
	ds_write_b128 v250, v[98:101] offset:3456
	ds_write_b128 v250, v[106:109] offset:4608
	ds_write_b128 v250, v[114:117] offset:5760
	ds_write_b128 v250, v[122:125] offset:6912
	ds_write_b128 v250, v[130:133] offset:8064
	ds_write_b128 v250, v[162:165] offset:9216
	ds_write_b128 v250, v[170:173] offset:10368
	ds_write_b128 v250, v[182:185] offset:11520
	ds_write_b128 v250, v[214:217] offset:12672
	ds_read_b128 v[222:225], v251
	ds_read_b128 v[230:233], v251 offset:2304
	ds_read_b128 v[238:241], v251 offset:4608
	ds_read_b128 v[138:141], v251 offset:6912
	ds_read_b128 v[246:249], v251 offset:9216
	ds_read_b128 v[66:69], v251 offset:11520
	ds_read_b128 v[226:229], v251 offset:64
	ds_read_b128 v[234:237], v251 offset:2368
	ds_read_b128 v[242:245], v251 offset:4672
	ds_read_b128 v[142:145], v251 offset:6976
	ds_read_b128 v[62:65], v251 offset:9280
	ds_read_b128 v[70:73], v251 offset:11584
	s_waitcnt lgkmcnt(6)
	v_mfma_f32_16x16x32_bf16 v[18:21], v[222:225], v[238:241], 0
	v_mfma_f32_16x16x32_bf16 v[22:25], v[222:225], v[138:141], 0
	v_mfma_f32_16x16x32_bf16 v[26:29], v[222:225], v[246:249], 0
	v_mfma_f32_16x16x32_bf16 v[30:33], v[222:225], v[66:69], 0
	v_mfma_f32_16x16x32_bf16 v[34:37], v[230:233], v[238:241], 0
	v_mfma_f32_16x16x32_bf16 v[38:41], v[230:233], v[138:141], 0
	v_mfma_f32_16x16x32_bf16 v[42:45], v[230:233], v[246:249], 0
	v_mfma_f32_16x16x32_bf16 v[46:49], v[230:233], v[66:69], 0
	s_waitcnt lgkmcnt(0)
	v_mfma_f32_16x16x32_bf16 v[18:21], v[226:229], v[242:245], v[18:21]
	v_mfma_f32_16x16x32_bf16 v[22:25], v[226:229], v[142:145], v[22:25]
	v_mfma_f32_16x16x32_bf16 v[26:29], v[226:229], v[62:65], v[26:29]
	v_mfma_f32_16x16x32_bf16 v[30:33], v[226:229], v[70:73], v[30:33]
	v_mfma_f32_16x16x32_bf16 v[34:37], v[234:237], v[242:245], v[34:37]
	v_mfma_f32_16x16x32_bf16 v[38:41], v[234:237], v[142:145], v[38:41]
	v_mfma_f32_16x16x32_bf16 v[42:45], v[234:237], v[62:65], v[42:45]
	v_mfma_f32_16x16x32_bf16 v[46:49], v[234:237], v[70:73], v[46:49]
	s_waitcnt vmcnt(0)
	ds_write_b128 v250, v[78:81]
	ds_write_b128 v250, v[86:89] offset:1152
	ds_write_b128 v250, v[94:97] offset:2304
	ds_write_b128 v250, v[102:105] offset:3456
	ds_write_b128 v250, v[110:113] offset:4608
	ds_write_b128 v250, v[118:121] offset:5760
	ds_write_b128 v250, v[126:129] offset:6912
	ds_write_b128 v250, v[134:137] offset:8064
	ds_write_b128 v250, v[166:169] offset:9216
	ds_write_b128 v250, v[178:181] offset:10368
	ds_write_b128 v250, v[210:213] offset:11520
	ds_write_b128 v250, v[218:221] offset:12672
	ds_read_b128 v[222:225], v251
	ds_read_b128 v[230:233], v251 offset:2304
	ds_read_b128 v[238:241], v251 offset:4608
	ds_read_b128 v[138:141], v251 offset:6912
	ds_read_b128 v[246:249], v251 offset:9216
	ds_read_b128 v[66:69], v251 offset:11520
	ds_read_b128 v[226:229], v251 offset:64
	ds_read_b128 v[234:237], v251 offset:2368
	ds_read_b128 v[242:245], v251 offset:4672
	ds_read_b128 v[142:145], v251 offset:6976
	ds_read_b128 v[62:65], v251 offset:9280
	ds_read_b128 v[70:73], v251 offset:11584
	s_waitcnt lgkmcnt(6)
	v_mfma_f32_16x16x32_bf16 v[18:21], v[222:225], v[238:241], v[18:21]
	v_mfma_f32_16x16x32_bf16 v[22:25], v[222:225], v[138:141], v[22:25]
	v_mfma_f32_16x16x32_bf16 v[26:29], v[222:225], v[246:249], v[26:29]
	v_mfma_f32_16x16x32_bf16 v[30:33], v[222:225], v[66:69], v[30:33]
	v_mfma_f32_16x16x32_bf16 v[34:37], v[230:233], v[238:241], v[34:37]
	v_mfma_f32_16x16x32_bf16 v[38:41], v[230:233], v[138:141], v[38:41]
	v_mfma_f32_16x16x32_bf16 v[42:45], v[230:233], v[246:249], v[42:45]
	v_mfma_f32_16x16x32_bf16 v[46:49], v[230:233], v[66:69], v[46:49]
	s_waitcnt lgkmcnt(0)
	v_mfma_f32_16x16x32_bf16 v[18:21], v[226:229], v[242:245], v[18:21]
	v_mfma_f32_16x16x32_bf16 v[22:25], v[226:229], v[142:145], v[22:25]
	v_mfma_f32_16x16x32_bf16 v[26:29], v[226:229], v[62:65], v[26:29]
	v_mfma_f32_16x16x32_bf16 v[30:33], v[226:229], v[70:73], v[30:33]
	v_mfma_f32_16x16x32_bf16 v[34:37], v[234:237], v[242:245], v[34:37]
	v_mfma_f32_16x16x32_bf16 v[38:41], v[234:237], v[142:145], v[38:41]
	v_mfma_f32_16x16x32_bf16 v[42:45], v[234:237], v[62:65], v[42:45]
	v_mfma_f32_16x16x32_bf16 v[46:49], v[234:237], v[70:73], v[46:49]
	s_waitcnt lgkmcnt(0)
	s_barrier
	s_nop 7
	s_nop 7
	v_add_u32_e32 v17, 0x1000, v16
	v_add_u32_e32 v10, 0x1400, v16
	ds_write2_b32 v16, v18, v22 offset1:16
	ds_write2_b32 v16, v19, v23 offset0:68 offset1:84
	ds_write2_b32 v16, v20, v24 offset0:136 offset1:152
	ds_write2_b32 v16, v21, v25 offset0:204 offset1:220
	ds_write2_b32 v16, v26, v30 offset0:32 offset1:48
	ds_write2_b32 v16, v27, v31 offset0:100 offset1:116
	ds_write2_b32 v16, v28, v32 offset0:168 offset1:184
	ds_write2_b32 v16, v29, v33 offset0:236 offset1:252
	ds_write2_b32 v17, v34, v38 offset0:64 offset1:80
	ds_write2_b32 v17, v35, v39 offset0:132 offset1:148
	ds_write2_b32 v17, v36, v40 offset0:200 offset1:216
	ds_write2_b32 v10, v37, v41 offset0:12 offset1:28
	ds_write2_b32 v17, v42, v46 offset0:96 offset1:112
	ds_write2_b32 v17, v43, v47 offset0:164 offset1:180
	ds_write2_b32 v17, v44, v48 offset0:232 offset1:248
	ds_write2_b32 v10, v45, v49 offset0:44 offset1:60
	s_waitcnt lgkmcnt(0)
	s_barrier
	s_and_saveexec_b64 s[0:1], vcc
	s_cbranch_execz .LBB0_102
	ds_read_b128 v[206:209], v15
	ds_read_b128 v[214:217], v15 offset:8704
	ds_read_b128 v[218:221], v15 offset:17408
	ds_read_b128 v[222:225], v15 offset:26112
	ds_read_b128 v[226:229], v15 offset:34816
	ds_read_b128 v[230:233], v15 offset:43520
	ds_read_b128 v[234:237], v15 offset:52224
	ds_read_b128 v[238:241], v15 offset:60928
	ds_read_b128 v[210:213], v15 offset:128
	ds_read_b128 v[242:245], v15 offset:8832
	ds_read_b128 v[246:249], v15 offset:17536
	ds_read_b128 v[162:165], v15 offset:26240
	ds_read_b128 v[166:169], v15 offset:34944
	ds_read_b128 v[170:173], v15 offset:43648
	ds_read_b128 v[178:181], v15 offset:52352
	s_waitcnt lgkmcnt(7)
	ds_read_b128 v[182:185], v15 offset:61056
	s_sub_i32 s25, 0, s25
	s_add_i32 s25, s25, s8
	v_pk_add_f32 v[10:11], v[208:209], 0 op_sel_hi:[1,0]
	v_pk_add_f32 v[12:13], v[206:207], 0 op_sel_hi:[1,0]
	v_pk_add_f32 v[10:11], v[10:11], v[216:217]
	v_pk_add_f32 v[12:13], v[12:13], v[214:215]
	v_pk_add_f32 v[10:11], v[10:11], v[220:221]
	v_pk_add_f32 v[12:13], v[12:13], v[218:219]
	v_pk_add_f32 v[10:11], v[10:11], v[224:225]
	v_pk_add_f32 v[12:13], v[12:13], v[222:223]
	v_pk_add_f32 v[10:11], v[10:11], v[228:229]
	v_pk_add_f32 v[12:13], v[12:13], v[226:227]
	v_pk_add_f32 v[10:11], v[10:11], v[232:233]
	v_pk_add_f32 v[12:13], v[12:13], v[230:231]
	v_pk_add_f32 v[10:11], v[10:11], v[236:237]
	v_pk_add_f32 v[12:13], v[12:13], v[234:235]
	v_pk_add_f32 v[8:9], v[10:11], v[240:241]
	v_pk_add_f32 v[10:11], v[12:13], v[238:239]
	s_waitcnt lgkmcnt(0)
	v_pk_add_f32 v[6:7], v[212:213], 0 op_sel_hi:[1,0]
	v_pk_add_f32 v[12:13], v[210:211], 0 op_sel_hi:[1,0]
	v_pk_add_f32 v[6:7], v[6:7], v[244:245]
	v_pk_add_f32 v[12:13], v[12:13], v[242:243]
	v_pk_add_f32 v[6:7], v[6:7], v[248:249]
	v_pk_add_f32 v[12:13], v[12:13], v[246:247]
	v_pk_add_f32 v[6:7], v[6:7], v[164:165]
	v_pk_add_f32 v[12:13], v[12:13], v[162:163]
	v_pk_add_f32 v[6:7], v[6:7], v[168:169]
	v_pk_add_f32 v[12:13], v[12:13], v[166:167]
	v_pk_add_f32 v[6:7], v[6:7], v[172:173]
	v_pk_add_f32 v[12:13], v[12:13], v[170:171]
	v_pk_add_f32 v[6:7], v[6:7], v[180:181]
	v_pk_add_f32 v[22:23], v[12:13], v[178:179]
	v_pk_add_f32 v[12:13], v[6:7], v[184:185]
	v_add_u32_e32 v6, s25, v14
	v_ashrrev_i32_e32 v7, 31, v6
	v_pk_add_f32 v[26:27], v[22:23], v[182:183]
	v_lshlrev_b64 v[22:23], 2, v[6:7]
	v_lshl_add_u64 v[18:19], s[40:41], 0, v[22:23]
	v_lshl_add_u64 v[22:23], s[2:3], 0, v[22:23]
	global_load_dwordx4 v[18:21], v[18:19], off
	s_nop 0
	global_load_dwordx4 v[22:25], v[22:23], off
	s_waitcnt vmcnt(1)
	v_add_f32_e32 v10, v10, v18
	v_add_f32_e32 v8, v8, v20
	s_waitcnt vmcnt(0)
	v_add_f32_e32 v17, v26, v22
	v_add_f32_e32 v12, v12, v24
	v_mul_f32_e32 v17, 0xbfb8aa3b, v17
	v_mul_f32_e32 v12, 0xbfb8aa3b, v12
	v_exp_f32_e32 v17, v17
	v_exp_f32_e32 v12, v12
	v_add_f32_e32 v11, v11, v19
	v_add_f32_e32 v17, 1.0, v17
	v_add_f32_e32 v12, 1.0, v12
	v_rcp_f32_e32 v17, v17
	v_rcp_f32_e32 v12, v12
	v_mul_f32_e32 v10, v10, v17
	v_add_f32_e32 v17, v27, v23
	v_mul_f32_e32 v12, v8, v12
	v_add_f32_e32 v8, v9, v21
	v_add_f32_e32 v9, v13, v25
	v_mul_f32_e32 v17, 0xbfb8aa3b, v17
	v_mul_f32_e32 v9, 0xbfb8aa3b, v9
	v_exp_f32_e32 v17, v17
	v_exp_f32_e32 v9, v9
	v_add_f32_e32 v17, 1.0, v17
	v_add_f32_e32 v9, 1.0, v9
	v_rcp_f32_e32 v17, v17
	v_rcp_f32_e32 v9, v9
	v_mul_f32_e32 v11, v11, v17
	v_mul_f32_e32 v9, v8, v9
	v_cvt_pk_bf16_f32 v8, v10, v11
	v_add_u32_e32 v10, s24, v0
	v_ashrrev_i32_e32 v11, 31, v10
	v_lshlrev_b64 v[10:11], 11, v[10:11]
	v_lshl_add_u64 v[10:11], s[20:21], 0, v[10:11]
	v_lshl_add_u64 v[6:7], v[6:7], 1, v[10:11]
	v_cvt_pk_bf16_f32 v9, v12, v9
	global_store_dwordx2 v[6:7], v[8:9], off
	s_branch .LBB0_102
